# S5: static priority raise for the scan waves (serial recurrence) over the MFMA waves
# speedup vs baseline: 1.0071x; 1.0003x over previous
; #define LAS __attribute__((address_space(3)))
; #define LDS_BARRIER() do { asm volatile("s_waitcnt lgkmcnt(0)" ::: "memory"); __builtin_amdgcn_s_barrier(); asm volatile("" ::: "memory"); } while (0)
; #define S5_DMA(s0) __builtin_amdgcn_global_load_lds((const unsigned*)(usrc + (size_t)(16 * (s0)) * DM), (LAS unsigned*)(uring + ((s0) & 7) * 512), 16, 0, 0)
; __device__ __forceinline__ void s5_phase(const Ctx& C, const bf16_t* U, bf16_t* Gout, const float* ABAR, const bf16_t* BB, const bf16_t* CM, const float* Dsk) {
;     ...
;     for (int task = C.wg; task < NBATCH * 32; task += C.G) {
;         const int b = task >> 5, g = (task & 31) * 4 + pw;
;         const size_t tokb = (size_t)b * SEQ;
;         LAS unsigned char* bub = C.lds + pw * 16384;
;         LAS unsigned char* hb = C.lds + 65536 + pw * (2 * S5_SUB * S5_HP);
;         __syncthreads();
;         if (role == 1) {
;     ...
;             const f32x2 ab = *(const f32x2*)(ABAR + ((size_t)g * 64 + lane) * 2);
;             float hr = 0.f, hi = 0.f;
;             LAS unsigned char* uring = C.lds + 100352 + pw * 4096;
;             const bf16_t* usrc = U + (tokb + 16 * (lane >> 5) + ((lane & 31) >> 1)) * DM + 16 * g + 8 * (lane & 1);
;     ...
;             S5_DMA(0); S5_DMA(2);
;             asm volatile("s_waitcnt vmcnt(0)" ::: "memory");
;             LDS_BARRIER();
;             for (int i = -1; i <= S5_NS; ++i) {
;                 if ((i & 1) && i + 5 < S5_NS) S5_DMA(i + 5);
.LBB0_173:
	s_setprio 0
	v_readlane_b32 s22, v254, 63
	s_add_i32 s1, s1, s22
	s_add_i32 s0, s0, s46
	s_cmpk_gt_i32 s1, 0xff
	s_cbranch_scc1 .LBB0_211
.LBB0_174:
	s_lshl_b32 s23, s1, 2
	s_ashr_i32 s22, s1, 5
	s_and_b32 s23, s23, 0x7c
	s_or_b32 s38, s23, s44
	s_ashr_i32 s23, s22, 31
	s_lshl_b64 s[72:73], s[22:23], 12
	s_mov_b64 s[80:81], -1
	s_and_b64 vcc, exec, s[70:71]
	s_barrier
	s_cbranch_vccz .LBB0_184
	v_mov_b32_e32 v3, s73
	v_or_b32_e32 v2, s72, v62
	v_readlane_b32 s40, v254, 11
	v_lshlrev_b64 v[2:3], 12, v[2:3]
	v_readlane_b32 s41, v254, 12
	s_lshl_b32 s96, s38, 5
	v_mov_b32_e32 v75, v65
	v_lshl_add_u64 v[2:3], s[40:41], 0, v[2:3]
	v_lshl_add_u64 v[2:3], v[2:3], 0, s[96:97]
	s_mov_b32 m0, s45
	v_lshl_add_u64 v[2:3], v[2:3], 0, v[74:75]
	s_mov_b64 s[80:81], 0x20000
	global_load_lds_dwordx4 v[2:3], off
	v_lshl_add_u64 v[4:5], v[2:3], 0, s[80:81]
	s_add_i32 m0, s45, 0x400
	v_lshl_or_b32 v0, s38, 9, v61
	global_load_lds_dwordx4 v[4:5], off
	global_load_dwordx2 v[0:1], v0, s[26:27]
	s_waitcnt vmcnt(0)
	s_mov_b64 s[80:81], 0x40000
	s_waitcnt lgkmcnt(0)
	s_barrier
	v_lshl_add_u64 v[2:3], v[2:3], 0, s[80:81]
	s_add_i32 m0, s45, 0x800
	s_lshl_b32 s39, s0, 5
	global_load_lds_dwordx4 v[2:3], off
	s_and_b32 s39, s39, 0xf80
	s_waitcnt vmcnt(1)
	s_or_b32 s39, s39, s47
	s_waitcnt lgkmcnt(0)
	s_barrier
	s_lshl_b64 s[22:23], s[22:23], 24
	s_or_b32 s22, s22, s39
	v_mov_b32_e32 v8, 0
	v_lshl_add_u64 v[6:7], v[72:73], 0, s[22:23]
	s_mov_b32 s39, 0
	s_movk_i32 s80, 0xa00
	v_mov_b32_e32 v9, v8
	s_waitcnt vmcnt(0)
	v_mov_b32_e32 v2, v1
	v_pk_mov_b32 v[4:5], v[0:1], v[0:1] op_sel:[1,0]
	s_setprio 1
	s_branch .LBB0_177
